# v5 + grid barrier: XCD leader publishes generation word before its own buffer_inv (acquire)
# baseline (speedup 1.0000x reference)
.LBB0_136:
	s_or_b64 exec, exec, s[4:5]
	s_mov_b64 s[4:5], exec
	v_mbcnt_lo_u32_b32 v0, s4, 0
	v_mbcnt_hi_u32_b32 v0, s5, v0
	v_cmp_eq_u32_e32 vcc, 0, v0
	s_waitcnt vmcnt(0)
	s_and_saveexec_b64 s[8:9], vcc
	s_cbranch_execz .LBB0_138
	s_bcnt1_i32_b64 s2, s[4:5]
	v_mov_b32_e32 v0, 0x2000
	v_mov_b32_e32 v1, s2
	global_atomic_add v0, v1, s[6:7] offset:1024
.LBB0_138:
	s_or_b64 exec, exec, s[8:9]
	buffer_inv sc1
	s_waitcnt vmcnt(0)

.LBB0_304:
	s_or_b64 exec, exec, s[4:5]
	s_mov_b64 s[4:5], exec
	v_mbcnt_lo_u32_b32 v0, s4, 0
	v_mbcnt_hi_u32_b32 v0, s5, v0
	v_cmp_eq_u32_e32 vcc, 0, v0
	s_waitcnt vmcnt(0)
	s_and_saveexec_b64 s[8:9], vcc
	s_cbranch_execz .LBB0_306
	s_bcnt1_i32_b64 s2, s[4:5]
	v_mov_b32_e32 v0, s2
	global_atomic_add v232, v0, s[6:7] offset:1024

.LBB0_433:
	s_or_b64 exec, exec, s[4:5]
	s_mov_b64 s[4:5], exec
	v_mbcnt_lo_u32_b32 v0, s4, 0
	v_mbcnt_hi_u32_b32 v0, s5, v0
	v_cmp_eq_u32_e32 vcc, 0, v0
	s_waitcnt vmcnt(0)
	s_and_saveexec_b64 s[8:9], vcc
	s_cbranch_execz .LBB0_145
	s_bcnt1_i32_b64 s2, s[4:5]
	v_mov_b32_e32 v0, s2
	global_atomic_add v232, v0, s[6:7] offset:1024
	s_branch .LBB0_145
